# P1 8x4 order with epilogue-type-grouped n chunks ({0-3},{8-11},{6,7,14,15},{4,5,12,13}) on top of nt output stores and nt weight loads
# baseline (speedup 1.0000x reference)
; __device__ void transpose_bf16(const float* __restrict__ src, int Kr, int Nc, u16* __restrict__ dst, const float* __restrict__ rowscale, char* lds, int bid, int nb) {
;     ...
;   for (int t = bid; t < tk * tn; t += nb) {
;     const int k0 = (t / tn) * 64, c0 = (t % tn) * 64;
; #pragma unroll
;     for (int i = 0; i < 2; ++i) {
;       const int r = (tid >> 4) + 32 * i, c4 = (tid & 15) * 4;
;       f32x4 v = *(const f32x4*)(src + (size_t)(k0 + r) * Nc + c0 + c4);
;       const float sc = rowscale ? rowscale[k0 + r] : 1.f;
.LBB0_19:
	s_mul_hi_i32 s12, s20, 0x3e0f83e1
	s_lshr_b32 s13, s12, 31
	s_ashr_i32 s12, s12, 4
	s_add_i32 s13, s12, s13
	s_lshl_b32 s12, s13, 6
	s_mulk_i32 s13, 0xef80
	s_add_i32 s14, s3, s13
	s_ashr_i32 s15, s14, 31
	v_lshl_add_u64 v[2:3], s[14:15], 2, v[12:13]
	v_or_b32_e32 v4, s12, v50
	v_mad_i64_i32 v[6:7], s[16:17], v4, s19, v[2:3]
	global_load_dwordx4 v[20:23], v[6:7], off nt
	v_add_u32_e32 v8, s12, v1
	v_mad_i64_i32 v[2:3], s[16:17], v8, s19, v[2:3]
	global_load_dwordx4 v[24:27], v[2:3], off nt
	s_and_b64 vcc, exec, s[4:5]
	s_cbranch_vccnz .Lp0_nosc_a
	v_ashrrev_i32_e32 v5, 31, v4
	v_lshl_add_u64 v[4:5], v[4:5], 2, s[8:9]
	global_load_dword v28, v[4:5], off
	s_ashr_i32 s13, s12, 31
	v_lshl_add_u64 v[6:7], s[12:13], 0, v[50:51]
	v_lshl_add_u64 v[6:7], v[6:7], 2, s[8:9]
	global_load_dword v29, v[6:7], off offset:128
	s_branch .Lp0_scdone_a

; __device__ void transpose_bf16(const float* __restrict__ src, int Kr, int Nc, u16* __restrict__ dst, const float* __restrict__ rowscale, char* lds, int bid, int nb) {
;     ...
;   for (int t = bid; t < tk * tn; t += nb) {
;     const int k0 = (t / tn) * 64, c0 = (t % tn) * 64;
; #pragma unroll
;     for (int i = 0; i < 2; ++i) {
;       const int r = (tid >> 4) + 32 * i, c4 = (tid & 15) * 4;
;       f32x4 v = *(const f32x4*)(src + (size_t)(k0 + r) * Nc + c0 + c4);
;       const float sc = rowscale ? rowscale[k0 + r] : 1.f;
; #pragma unroll
;       for (int e = 0; e < 4; ++e) ts[(c4 + e) * 65 + r] = v[e] * sc;
.Lp0_loop:
	s_waitcnt vmcnt(1)
	v_mul_f32_e32 v30, v20, v28
	v_mul_f32_e32 v31, v21, v28
	v_mul_f32_e32 v32, v22, v28
	v_mul_f32_e32 v33, v23, v28
	v_mul_f32_e32 v34, v24, v29
	v_mul_f32_e32 v35, v25, v29
	v_mul_f32_e32 v36, v26, v29
	v_mul_f32_e32 v37, v27, v29
	ds_write2_b32 v16, v30, v31 offset1:65
	ds_write2_b32 v16, v32, v33 offset0:130 offset1:195
	ds_write2_b32 v16, v34, v35 offset0:32 offset1:97
	ds_write2_b32 v16, v36, v37 offset0:162 offset1:227
	s_add_i32 s20, s20, s50
	s_add_i32 s3, s3, s18
	s_mov_b32 s90, 0
	s_cmpk_lt_i32 s20, 0x420
	s_cbranch_scc0 .Lp0_nonext
	s_mov_b32 s90, 1
	s_mul_hi_i32 s12, s20, 0x3e0f83e1
	s_lshr_b32 s13, s12, 31
	s_ashr_i32 s12, s12, 4
	s_add_i32 s13, s12, s13
	s_lshl_b32 s12, s13, 6
	s_mulk_i32 s13, 0xef80
	s_add_i32 s14, s3, s13
	s_ashr_i32 s15, s14, 31
	v_lshl_add_u64 v[2:3], s[14:15], 2, v[12:13]
	v_or_b32_e32 v4, s12, v50
	v_mad_i64_i32 v[6:7], s[16:17], v4, s19, v[2:3]
	global_load_dwordx4 v[20:23], v[6:7], off nt
	v_add_u32_e32 v8, s12, v1
	v_mad_i64_i32 v[2:3], s[16:17], v8, s19, v[2:3]
	global_load_dwordx4 v[24:27], v[2:3], off nt
	s_and_b64 vcc, exec, s[4:5]
	s_cbranch_vccnz .Lp0_nosc_b
	v_ashrrev_i32_e32 v5, 31, v4
	v_lshl_add_u64 v[4:5], v[4:5], 2, s[8:9]
	global_load_dword v28, v[4:5], off
	s_ashr_i32 s13, s12, 31
	v_lshl_add_u64 v[6:7], s[12:13], 0, v[50:51]
	v_lshl_add_u64 v[6:7], v[6:7], 2, s[8:9]
	global_load_dword v29, v[6:7], off offset:128
	s_branch .Lp0_scdone_b

; __device__ __forceinline__ unsigned pk2(float lo, float hi) { f32x2_t v = {lo, hi}; bf16x2_t b = __builtin_convertvector(v, bf16x2_t); return __builtin_bit_cast(unsigned, b); }
; __device__ void transpose_bf16(const float* __restrict__ src, int Kr, int Nc, u16* __restrict__ dst, const float* __restrict__ rowscale, char* lds, int bid, int nb) {
;     ...
;   for (int t = bid; t < tk * tn; t += nb) {
;     const int k0 = (t / tn) * 64, c0 = (t % tn) * 64;
; #pragma unroll
;     for (int i = 0; i < 2; ++i) {
;       const int r = (tid >> 4) + 32 * i, c4 = (tid & 15) * 4;
;       f32x4 v = *(const f32x4*)(src + (size_t)(k0 + r) * Nc + c0 + c4);
;       const float sc = rowscale ? rowscale[k0 + r] : 1.f;
; #pragma unroll
;       for (int e = 0; e < 4; ++e) ts[(c4 + e) * 65 + r] = v[e] * sc;
;     }
;     __syncthreads();
;     {
;       const int c = tid >> 3, ch = tid & 7;
;       const float* tp = ts + c * 65 + ch * 8;
;       u32x4 w; w.x = pk2(tp[0], tp[1]); w.y = pk2(tp[2], tp[3]); w.z = pk2(tp[4], tp[5]); w.w = pk2(tp[6], tp[7]);
;       *(u32x4*)(dst + (size_t)(c0 + c) * Kr + k0 + ch * 8) = w;
;     }
;     __syncthreads();
.LBB0_28:
	s_ashr_i32 s8, s7, 31
	s_lshr_b32 s8, s8, 28
	s_add_i32 s8, s7, s8
	s_ashr_i32 s9, s8, 4
	s_lshl_b32 s8, s9, 6
	s_lshl_b32 s9, s9, 10
	s_sub_i32 s10, s3, s9
	v_or_b32_e32 v8, s8, v50
	v_add_u32_e32 v10, s8, v1
	s_ashr_i32 s11, s10, 31
	v_ashrrev_i32_e32 v9, 31, v8
	v_ashrrev_i32_e32 v11, 31, v10
	v_lshl_add_u64 v[12:13], s[10:11], 2, v[4:5]
	v_lshlrev_b64 v[8:9], 12, v[8:9]
	v_lshlrev_b64 v[10:11], 12, v[10:11]
	v_lshl_add_u64 v[16:17], v[12:13], 0, v[8:9]
	v_lshl_add_u64 v[18:19], v[12:13], 0, v[10:11]
	global_load_dwordx4 v[8:11], v[16:17], off nt
	global_load_dwordx4 v[12:15], v[18:19], off nt
	v_add_u32_e32 v16, s10, v240
	v_ashrrev_i32_e32 v17, 31, v16
	v_lshlrev_b64 v[16:17], 11, v[16:17]
	s_ashr_i32 s9, s8, 31
	v_lshl_add_u64 v[16:17], s[4:5], 0, v[16:17]
	s_add_i32 s7, s7, s50
	s_add_i32 s3, s3, s6
	v_lshl_add_u64 v[16:17], s[8:9], 1, v[16:17]
	s_cmpk_lt_i32 s7, 0x100
	v_lshl_add_u64 v[16:17], v[16:17], 0, v[2:3]
	s_waitcnt vmcnt(0)
	ds_write2_b32 v7, v8, v12 offset1:32
	ds_write2_b32 v7, v9, v13 offset0:65 offset1:97
	ds_write2_b32 v7, v10, v14 offset0:130 offset1:162
	ds_write2_b32 v7, v11, v15 offset0:195 offset1:227
	s_waitcnt lgkmcnt(0)
	s_barrier
	ds_read2_b32 v[8:9], v6 offset1:1
	ds_read2_b32 v[10:11], v6 offset0:2 offset1:3
	ds_read2_b32 v[12:13], v6 offset0:4 offset1:5
	ds_read2_b32 v[14:15], v6 offset0:6 offset1:7
	s_waitcnt lgkmcnt(3)
	v_cvt_pk_bf16_f32 v8, v8, v9
	s_waitcnt lgkmcnt(2)
	v_cvt_pk_bf16_f32 v9, v10, v11
	s_waitcnt lgkmcnt(1)
	v_cvt_pk_bf16_f32 v10, v12, v13
	s_waitcnt lgkmcnt(0)
	v_cvt_pk_bf16_f32 v11, v14, v15
	global_store_dwordx4 v[16:17], v[8:11], off
	s_barrier
	s_cbranch_scc1 .LBB0_28

;     ...
;   for (int Lx = jx; Lx < (NMT / 8) * NNT; Lx += nbx) {
;     const int grp = Lx / (2 * NNT), gi = Lx % (2 * NNT);
;     const int mt = xcd * (NMT / 8) + 2 * grp + (gi & 1), nt = gi >> 1;
.Lp1_map_full:
	s_lshr_b32 s34, s58, 5
	s_and_b32 s35, s58, 31
	s_and_b32 s6, s35, 7
	s_lshr_b32 s7, s34, 2
	s_lshl_b32 s7, s7, 3
	s_add_i32 s6, s6, s7
	s_and_b32 s34, s34, 3
	s_lshl_b32 s94, s34, 2
	s_lshr_b32 s94, 0x4680, s94
	s_and_b32 s94, s94, 15
	s_cmp_lt_u32 s34, 2
	s_cselect_b32 s95, 2, 8
	s_lshr_b32 s7, s35, 3
	s_lshr_b32 s34, s7, 1
	s_mul_i32 s34, s34, s95
	s_and_b32 s7, s7, 1
	s_add_i32 s7, s7, s34
	s_add_i32 s7, s7, s94
